# ssd_out: both per-head MFMA sections (masked-product x X and C x prefix-state) read their LDS fragments up front with counted waits
# speedup vs baseline: 1.0054x; 1.0039x over previous
; DI unsigned pk2(float lo, float hi) { unsigned r; asm volatile("v_cvt_pk_bf16_f32 %0, %1, %2" : "=v"(r) : "v"(lo), "v"(hi)); return r; }
; DI float bflo(unsigned u) { return __uint_as_float(u << 16); }
; DI float bfhi(unsigned u) { return __uint_as_float(u & 0xffff0000u); }
; DI float silu_f(float x) { return x * __builtin_amdgcn_rcpf(1.0f + __expf(-x)); }
; DI f32x4 mmaT(bf16x8 a_m, bf16x8 b_n, f32x4 c) { return __builtin_amdgcn_mfma_f32_16x16x32_bf16(b_n, a_m, c, 0, 0, 0); }
; DI void ssd_out_unit(const Params& p, int layer, int hf, int bl, int c, unsigned char* shm, int tid, bool dry = false) {
;     ...
; #pragma unroll
;       for (int ks = 0; ks < 4; ++ks) {
;         const bf16x8 a = ldf(sC, LD, 16 * wid, 32 * ks, fr, fq);
; #pragma unroll
;         for (int m = 0; m < 4; ++m) y2[m] = mmaT(a, ldf(sSp, LD, 16 * m, 32 * ks, fr, fq), y2[m]);
;       }
;       const float ei = __expf(ac_i), Dh = p.d_skip[layer * 16 + h];
; #pragma unroll
;       for (int m = 0; m < 4; ++m) {
;         const uint2 zv = zv4[m];
;         const uint2 xv = *(const uint2*)(sX + i_row * LXS + 16 * m + 4 * fq);
;         const float zz[4] = {bflo(zv.x), bfhi(zv.x), bflo(zv.y), bfhi(zv.y)};
;         const float xs[4] = {bflo(xv.x), bfhi(xv.x), bflo(xv.y), bfhi(xv.y)};
;         float r[4];
; #pragma unroll
;         for (int j = 0; j < 4; ++j) {
;           const float v = (y[m][j] + ei * y2[m][j] + Dh * xs[j]) * silu_f(zz[j]);
;           r[j] = v; ssq += v * v;
;         }
;         uint2 w; w.x = pk2(r[0], r[1]); w.y = pk2(r[2], r[3]);
;         if (!dry || ssq == 1.2345e-30f) *(uint2*)(zp + 16 * m) = w;
;       }
.LBB0_520:
	s_or_b64 exec, exec, s[30:31]
	v_add_u32_e32 v116, v128, v86
	ds_read_b128 v[60:63], v116
	ds_read_b128 v[76:79], v132
	ds_read_b128 v[72:75], v132 offset:4352
	ds_read_b128 v[68:71], v132 offset:8704
	ds_read_b128 v[136:139], v132 offset:13056
	ds_read_b128 v[144:147], v116 offset:64
	ds_read_b128 v[148:151], v132 offset:64
	ds_read_b128 v[152:155], v132 offset:4416
	ds_read_b128 v[156:159], v132 offset:8768
	ds_read_b128 v[172:175], v132 offset:13120
	ds_read_b128 v[176:179], v116 offset:128
	ds_read_b128 v[180:183], v132 offset:128
	ds_read_b128 v[184:187], v132 offset:4480
	ds_read_b128 v[188:191], v132 offset:8832
	ds_read_b128 v[236:239], v132 offset:13184
	v_readlane_b32 s2, v254, 24
	s_add_i32 s2, s44, s2
	v_readlane_b32 s8, v252, 24
	s_add_i32 s43, s43, 1
	s_lshl_b64 s[30:31], s[2:3], 2
	v_readlane_b32 s14, v252, 30
	v_readlane_b32 s15, v252, 31
	s_add_u32 s30, s14, s30
	s_addc_u32 s31, s15, s31
	v_mul_f32_e32 v112, 0x3fb8aa3b, v112
	v_exp_f32_e32 v112, v112
	s_waitcnt lgkmcnt(13)
	v_mfma_f32_16x16x32_bf16 v[76:79], v[76:79], v[60:63], 0
	s_waitcnt lgkmcnt(12)
	v_mfma_f32_16x16x32_bf16 v[72:75], v[72:75], v[60:63], 0
	s_waitcnt lgkmcnt(11)
	v_mfma_f32_16x16x32_bf16 v[68:71], v[68:71], v[60:63], 0
	s_waitcnt lgkmcnt(10)
	v_mfma_f32_16x16x32_bf16 v[60:63], v[136:139], v[60:63], 0
	ds_read_b128 v[240:243], v116 offset:192
	ds_read_b128 v[244:247], v132 offset:192
	ds_read_b128 v[248:251], v132 offset:4544
	ds_read_b128 v[140:143], v132 offset:8896
	ds_read_b128 v[136:139], v132 offset:13248
	s_waitcnt vmcnt(3)
	v_lshlrev_b32_e32 v135, 16, v118
	v_and_b32_e32 v118, 0xffff0000, v118
	s_cmp_eq_u32 s43, 8
	v_readlane_b32 s9, v252, 25
	v_readlane_b32 s10, v252, 26
	v_readlane_b32 s11, v252, 27
	v_readlane_b32 s12, v252, 28
	v_readlane_b32 s13, v252, 29
	v_readlane_b32 s16, v252, 32
	v_readlane_b32 s17, v252, 33
	v_readlane_b32 s18, v252, 34
	v_readlane_b32 s19, v252, 35
	v_readlane_b32 s20, v252, 36
	v_readlane_b32 s21, v252, 37
	v_readlane_b32 s22, v252, 38
	v_readlane_b32 s23, v252, 39
	global_load_dword v116, v161, s[30:31]
	s_waitcnt lgkmcnt(13)
	v_mfma_f32_16x16x32_bf16 v[76:79], v[148:151], v[144:147], v[76:79]
	s_waitcnt lgkmcnt(12)
	v_mfma_f32_16x16x32_bf16 v[72:75], v[152:155], v[144:147], v[72:75]
	s_waitcnt lgkmcnt(11)
	v_mfma_f32_16x16x32_bf16 v[68:71], v[156:159], v[144:147], v[68:71]
	s_waitcnt lgkmcnt(10)
	v_mfma_f32_16x16x32_bf16 v[60:63], v[172:175], v[144:147], v[60:63]
	s_waitcnt lgkmcnt(8)
	v_mfma_f32_16x16x32_bf16 v[76:79], v[180:183], v[176:179], v[76:79]
	s_waitcnt lgkmcnt(7)
	v_mfma_f32_16x16x32_bf16 v[72:75], v[184:187], v[176:179], v[72:75]
	s_waitcnt lgkmcnt(6)
	v_mfma_f32_16x16x32_bf16 v[68:71], v[188:191], v[176:179], v[68:71]
	s_waitcnt lgkmcnt(5)
	v_mfma_f32_16x16x32_bf16 v[60:63], v[236:239], v[176:179], v[60:63]
	s_waitcnt lgkmcnt(3)
	v_mfma_f32_16x16x32_bf16 v[76:79], v[244:247], v[240:243], v[76:79]
	s_waitcnt lgkmcnt(2)
	v_mfma_f32_16x16x32_bf16 v[72:75], v[248:251], v[240:243], v[72:75]
	s_waitcnt lgkmcnt(1)
	v_mfma_f32_16x16x32_bf16 v[68:71], v[140:143], v[240:243], v[68:71]
	s_waitcnt lgkmcnt(0)
	v_mfma_f32_16x16x32_bf16 v[60:63], v[136:139], v[240:243], v[60:63]
	s_nop 7
	s_nop 3
	v_fmac_f32_e32 v64, v112, v76
	v_mul_f32_e32 v76, 0xbfb8aa3b, v135
	v_exp_f32_e32 v76, v76
	v_fmac_f32_e32 v65, v112, v77
	ds_read_b64 v[136:137], v87
	v_add_f32_e32 v76, 1.0, v76
	v_rcp_f32_e32 v76, v76
	v_lshlrev_b32_e32 v138, 16, v119
	v_fmac_f32_e32 v66, v112, v78
	s_waitcnt lgkmcnt(0)
	v_lshlrev_b32_e32 v139, 16, v136
	v_mul_f32_e32 v76, v76, v135
	v_and_b32_e32 v136, 0xffff0000, v136
	v_lshlrev_b32_e32 v140, 16, v137
	v_and_b32_e32 v119, 0xffff0000, v119
	v_and_b32_e32 v137, 0xffff0000, v137
	v_fmac_f32_e32 v67, v112, v79
	v_pk_fma_f32 v[56:57], v[112:113], v[72:73], v[56:57] op_sel_hi:[0,1,1]
	s_waitcnt vmcnt(3)
	v_and_b32_e32 v77, 0xffff0000, v115
	v_pk_fma_f32 v[58:59], v[112:113], v[74:75], v[58:59] op_sel_hi:[0,1,1]
	v_pk_fma_f32 v[52:53], v[112:113], v[68:69], v[52:53] op_sel_hi:[0,1,1]
	v_pk_fma_f32 v[54:55], v[112:113], v[70:71], v[54:55] op_sel_hi:[0,1,1]
	v_pk_fma_f32 v[48:49], v[112:113], v[60:61], v[48:49] op_sel_hi:[0,1,1]
	v_pk_fma_f32 v[50:51], v[112:113], v[62:63], v[50:51] op_sel_hi:[0,1,1]
	s_waitcnt vmcnt(0)
; DI unsigned pk2(float lo, float hi) { unsigned r; asm volatile("v_cvt_pk_bf16_f32 %0, %1, %2" : "=v"(r) : "v"(lo), "v"(hi)); return r; }
; DI float bflo(unsigned u) { return __uint_as_float(u << 16); }
; DI float bfhi(unsigned u) { return __uint_as_float(u & 0xffff0000u); }
; DI float silu_f(float x) { return x * __builtin_amdgcn_rcpf(1.0f + __expf(-x)); }
; DI void ssd_out_unit(const Params& p, int layer, int hf, int bl, int c, unsigned char* shm, int tid, bool dry = false) {
;     ...
;       const float ei = __expf(ac_i), Dh = p.d_skip[layer * 16 + h];
; #pragma unroll
;       for (int m = 0; m < 4; ++m) {
;         const uint2 zv = zv4[m];
;         const uint2 xv = *(const uint2*)(sX + i_row * LXS + 16 * m + 4 * fq);
;         const float zz[4] = {bflo(zv.x), bfhi(zv.x), bflo(zv.y), bfhi(zv.y)};
;         const float xs[4] = {bflo(xv.x), bfhi(xv.x), bflo(xv.y), bfhi(xv.y)};
;         float r[4];
; #pragma unroll
;         for (int j = 0; j < 4; ++j) {
;           const float v = (y[m][j] + ei * y2[m][j] + Dh * xs[j]) * silu_f(zz[j]);
;           r[j] = v; ssq += v * v;
;         }
;         uint2 w; w.x = pk2(r[0], r[1]); w.y = pk2(r[2], r[3]);
;         if (!dry || ssq == 1.2345e-30f) *(uint2*)(zp + 16 * m) = w;
;       }
;       __syncthreads();
;     }
	v_fmac_f32_e32 v64, v116, v139
	v_mul_f32_e32 v64, v76, v64
	v_mul_f32_e32 v76, 0xbfb8aa3b, v118
	v_exp_f32_e32 v76, v76
	v_fmac_f32_e32 v65, v116, v136
	v_fmac_f32_e32 v66, v116, v140
	v_fmac_f32_e32 v134, v64, v64
	v_add_f32_e32 v76, 1.0, v76
	v_rcp_f32_e32 v76, v76
	v_fmac_f32_e32 v67, v116, v137
	v_mul_f32_e32 v76, v76, v118
	v_mul_f32_e32 v65, v76, v65
	v_mul_f32_e32 v76, 0xbfb8aa3b, v138
	v_exp_f32_e32 v76, v76
	v_fmac_f32_e32 v134, v65, v65
	v_cvt_pk_bf16_f32 v64, v64, v65
	v_add_f32_e32 v76, 1.0, v76
	v_rcp_f32_e32 v76, v76
	s_nop 0
	v_mul_f32_e32 v76, v76, v138
	v_mul_f32_e32 v66, v76, v66
	v_mul_f32_e32 v76, 0xbfb8aa3b, v119
	v_exp_f32_e32 v76, v76
	v_fmac_f32_e32 v134, v66, v66
	v_add_f32_e32 v76, 1.0, v76
	v_rcp_f32_e32 v76, v76
	s_nop 0
	v_mul_f32_e32 v76, v76, v119
	v_mul_f32_e32 v67, v76, v67
	v_fmac_f32_e32 v134, v67, v67
	v_cvt_pk_bf16_f32 v65, v66, v67
	v_lshlrev_b32_e32 v66, 16, v114
	v_and_b32_e32 v67, 0xffff0000, v114
	v_mul_f32_e32 v114, 0xbfb8aa3b, v66
	v_mul_f32_e32 v72, 0xbfb8aa3b, v67
	v_exp_f32_e32 v114, v114
	v_exp_f32_e32 v72, v72
	global_store_dwordx2 v[106:107], v[64:65], off
	ds_read_b64 v[64:65], v87 offset:32
	v_add_f32_e32 v114, 1.0, v114
	v_add_f32_e32 v72, 1.0, v72
	v_lshlrev_b32_e32 v76, 16, v115
	v_rcp_f32_e32 v114, v114
	v_rcp_f32_e32 v115, v72
	s_waitcnt lgkmcnt(0)
	v_lshlrev_b32_e32 v78, 16, v64
	v_and_b32_e32 v79, 0xffff0000, v64
	v_pk_fma_f32 v[56:57], v[116:117], v[78:79], v[56:57] op_sel_hi:[0,1,1]
	v_pk_mul_f32 v[66:67], v[114:115], v[66:67]
	v_lshlrev_b32_e32 v64, 16, v65
	v_pk_mul_f32 v[56:57], v[66:67], v[56:57]
	v_and_b32_e32 v65, 0xffff0000, v65
	v_pk_mul_f32 v[66:67], v[56:57], v[56:57]
	v_pk_fma_f32 v[58:59], v[116:117], v[64:65], v[58:59] op_sel_hi:[0,1,1]
	v_add_f32_e32 v66, v134, v66
	v_add_f32_e32 v72, v67, v66
	v_mul_f32_e32 v66, 0xbfb8aa3b, v76
	v_mul_f32_e32 v64, 0xbfb8aa3b, v77
	v_exp_f32_e32 v66, v66
	v_exp_f32_e32 v64, v64
	v_cvt_pk_bf16_f32 v56, v56, v57
	v_add_f32_e32 v66, 1.0, v66
	v_add_f32_e32 v64, 1.0, v64
	v_rcp_f32_e32 v66, v66
	v_rcp_f32_e32 v67, v64
	s_nop 0
	v_pk_mul_f32 v[64:65], v[66:67], v[76:77]
	s_nop 0
	v_pk_mul_f32 v[58:59], v[64:65], v[58:59]
	s_nop 0
	v_cvt_pk_bf16_f32 v57, v58, v59
	global_store_dwordx2 v[106:107], v[56:57], off offset:32
	ds_read_b64 v[56:57], v87 offset:64
	v_pk_mul_f32 v[64:65], v[58:59], v[58:59]
	v_lshlrev_b32_e32 v58, 16, v110
	v_and_b32_e32 v59, 0xffff0000, v110
	v_add_f32_e32 v64, v64, v72
	s_waitcnt lgkmcnt(0)
	v_lshlrev_b32_e32 v66, 16, v56
	v_and_b32_e32 v67, 0xffff0000, v56
	v_mul_f32_e32 v72, 0xbfb8aa3b, v58
	v_pk_fma_f32 v[52:53], v[116:117], v[66:67], v[52:53] op_sel_hi:[0,1,1]
	v_mul_f32_e32 v66, 0xbfb8aa3b, v59
	v_exp_f32_e32 v72, v72
	v_exp_f32_e32 v66, v66
	v_add_f32_e32 v74, v65, v64
	v_lshlrev_b32_e32 v64, 16, v111
	v_add_f32_e32 v72, 1.0, v72
	v_add_f32_e32 v66, 1.0, v66
	v_rcp_f32_e32 v72, v72
	v_rcp_f32_e32 v73, v66
	v_and_b32_e32 v65, 0xffff0000, v111
	v_lshlrev_b32_e32 v56, 16, v57
	v_and_b32_e32 v57, 0xffff0000, v57
	v_pk_mul_f32 v[58:59], v[72:73], v[58:59]
	v_pk_fma_f32 v[54:55], v[116:117], v[56:57], v[54:55] op_sel_hi:[0,1,1]
	v_pk_mul_f32 v[52:53], v[58:59], v[52:53]
	v_mul_f32_e32 v56, 0xbfb8aa3b, v65
	v_pk_mul_f32 v[58:59], v[52:53], v[52:53]
	v_exp_f32_e32 v56, v56
	v_add_f32_e32 v58, v74, v58
	v_add_f32_e32 v66, v59, v58
	v_mul_f32_e32 v58, 0xbfb8aa3b, v64
	v_exp_f32_e32 v58, v58
	v_add_f32_e32 v56, 1.0, v56
	v_rcp_f32_e32 v59, v56
	v_cvt_pk_bf16_f32 v52, v52, v53
	v_add_f32_e32 v58, 1.0, v58
	v_rcp_f32_e32 v58, v58
	s_nop 0
	v_pk_mul_f32 v[56:57], v[58:59], v[64:65]
	s_nop 0
	v_pk_mul_f32 v[54:55], v[56:57], v[54:55]
	s_nop 0
	v_cvt_pk_bf16_f32 v53, v54, v55
	global_store_dwordx2 v[106:107], v[52:53], off offset:64
	ds_read_b64 v[52:53], v87 offset:96
	v_pk_mul_f32 v[56:57], v[54:55], v[54:55]
	v_lshlrev_b32_e32 v54, 16, v108
	v_and_b32_e32 v55, 0xffff0000, v108
	v_mul_f32_e32 v64, 0xbfb8aa3b, v54
	s_waitcnt lgkmcnt(0)
	v_lshlrev_b32_e32 v58, 16, v52
	v_and_b32_e32 v59, 0xffff0000, v52
	v_pk_fma_f32 v[48:49], v[116:117], v[58:59], v[48:49] op_sel_hi:[0,1,1]
	v_mul_f32_e32 v58, 0xbfb8aa3b, v55
	v_exp_f32_e32 v64, v64
	v_exp_f32_e32 v58, v58
	v_add_f32_e32 v56, v56, v66
	v_add_f32_e32 v66, v57, v56
	v_add_f32_e32 v64, 1.0, v64
	v_add_f32_e32 v58, 1.0, v58
	v_rcp_f32_e32 v64, v64
	v_rcp_f32_e32 v65, v58
	v_lshlrev_b32_e32 v56, 16, v109
	v_and_b32_e32 v57, 0xffff0000, v109
	v_lshlrev_b32_e32 v52, 16, v53
	v_pk_mul_f32 v[54:55], v[64:65], v[54:55]
	v_and_b32_e32 v53, 0xffff0000, v53
	v_pk_mul_f32 v[48:49], v[54:55], v[48:49]
	v_pk_fma_f32 v[50:51], v[116:117], v[52:53], v[50:51] op_sel_hi:[0,1,1]
	v_pk_mul_f32 v[54:55], v[48:49], v[48:49]
	v_mul_f32_e32 v52, 0xbfb8aa3b, v57
	v_add_f32_e32 v54, v66, v54
	v_add_f32_e32 v58, v55, v54
	v_mul_f32_e32 v54, 0xbfb8aa3b, v56
	v_exp_f32_e32 v54, v54
	v_exp_f32_e32 v52, v52
	v_cvt_pk_bf16_f32 v48, v48, v49
	v_add_f32_e32 v54, 1.0, v54
	v_add_f32_e32 v52, 1.0, v52
	v_rcp_f32_e32 v54, v54
	v_rcp_f32_e32 v55, v52
	s_nop 0
	v_pk_mul_f32 v[52:53], v[54:55], v[56:57]
	s_nop 0
	v_pk_mul_f32 v[50:51], v[52:53], v[50:51]
	s_nop 0
	v_pk_mul_f32 v[52:53], v[50:51], v[50:51]
	v_cvt_pk_bf16_f32 v49, v50, v51
	global_store_dwordx2 v[106:107], v[48:49], off offset:96
	v_add_f32_e32 v52, v52, v58
	v_add_f32_e32 v134, v53, v52
	s_barrier
	s_cbranch_scc1 .LBB0_502

; DI f32x4 mmaT(bf16x8 a_m, bf16x8 b_n, f32x4 c) { return __builtin_amdgcn_mfma_f32_16x16x32_bf16(b_n, a_m, c, 0, 0, 0); }
; DI void ssd_out_unit(const Params& p, int layer, int hf, int bl, int c, unsigned char* shm, int tid, bool dry = false) {
;     ...
;       const int nks = (wid >> 1) + 1;
;       for (int ks = 0; ks < nks; ++ks) {
;         const bf16x8 a = ldf(sM, LD, 16 * wid, 32 * ks, fr, fq);
; #pragma unroll
;         for (int m = 0; m < 4; ++m) y[m] = mmaT(a, frag_tr(sX, LXS, 32 * ks, 16 * m, fr, fq), y[m]);
;       }
.LBB0_567:
	v_add_u32_e32 v63, 32, v61
	ds_read_b128 v[68:71], v63
	v_add_u32_e32 v63, 32, v60
	v_add_u32_e32 v72, 0x11000, v63
	ds_read_b64_tr_b16 v[144:145], v72
	ds_read_b64_tr_b16 v[146:147], v72 offset:576
	ds_read_b64_tr_b16 v[148:149], v72 offset:32
	ds_read_b64_tr_b16 v[150:151], v72 offset:608
	ds_read_b64_tr_b16 v[152:153], v72 offset:64
	ds_read_b64_tr_b16 v[154:155], v72 offset:640
	ds_read_b64_tr_b16 v[156:157], v72 offset:96
	ds_read_b64_tr_b16 v[158:159], v72 offset:672
	v_add_u32_e32 v62, -1, v62
	v_cmp_eq_u32_e32 vcc, 0, v62
	v_add_u32_e32 v61, 64, v61
	v_add_u32_e32 v60, 0x1200, v60
	s_or_b64 s[34:35], vcc, s[34:35]
	s_waitcnt lgkmcnt(6)
	v_mfma_f32_16x16x32_bf16 v[64:67], v[144:147], v[68:71], v[64:67]
	s_waitcnt lgkmcnt(4)
	v_mfma_f32_16x16x32_bf16 v[56:59], v[148:151], v[68:71], v[56:59]
	s_waitcnt lgkmcnt(2)
	v_mfma_f32_16x16x32_bf16 v[52:55], v[152:155], v[68:71], v[52:55]
	s_waitcnt lgkmcnt(0)
	v_mfma_f32_16x16x32_bf16 v[48:51], v[156:159], v[68:71], v[48:51]
	s_andn2_b64 exec, exec, s[34:35]
	s_cbranch_execnz .LBB0_567
	s_or_b64 exec, exec, s[34:35]
	s_branch .LBB0_520
